# v22
# speedup vs baseline: 1.0067x; 1.0053x over previous
.LBB0_1198:
	s_add_u32 s70, s8, 0xfff80080
	s_addc_u32 s71, s9, -1
	s_add_i32 s77, 0, 0x10000
	v_add_u32_e32 v140, s77, v225
	ds_read_b128 v[128:131], v140
	ds_read_b128 v[132:135], v140 offset:1024
	ds_read_b128 v[136:139], v140 offset:2048
	ds_read_b128 v[140:143], v140 offset:3072
	s_cmp_eq_u32 s76, 28
	s_cselect_b32 s73, s5, s71
	s_cselect_b32 s72, s4, s70
	s_cselect_b32 s71, s7, s75
	s_cselect_b32 s70, s6, s35
	s_add_i32 m0, s84, 0xc000
	ds_read_b128 v[144:147], v226
	ds_read_b128 v[148:151], v226 offset:1024
	ds_read_b128 v[152:155], v226 offset:2048
	ds_read_b128 v[156:159], v226 offset:3072
	ds_read_b128 v[160:163], v226 offset:4096
	ds_read_b128 v[164:167], v226 offset:5120
	ds_read_b128 v[168:171], v226 offset:6144
	ds_read_b128 v[172:175], v226 offset:7168
	global_load_lds_dwordx4 v190, s[8:9]
	s_add_i32 m0, s84, 0xe000
	s_nop 0
	global_load_lds_dwordx4 v188, s[8:9]
	s_waitcnt lgkmcnt(8)
	s_barrier
	s_waitcnt lgkmcnt(0)
	s_waitcnt lgkmcnt(0)
	v_mfma_f32_16x16x32_bf16 v[124:127], v[128:131], v[144:147], v[124:127]
	v_mfma_f32_16x16x32_bf16 v[60:63], v[136:139], v[144:147], v[60:63]
	v_mfma_f32_16x16x32_bf16 v[116:119], v[128:131], v[152:155], v[116:119]
	v_mfma_f32_16x16x32_bf16 v[52:55], v[136:139], v[152:155], v[52:55]
	v_mfma_f32_16x16x32_bf16 v[108:111], v[128:131], v[160:163], v[108:111]
	v_mfma_f32_16x16x32_bf16 v[44:47], v[136:139], v[160:163], v[44:47]
	v_mfma_f32_16x16x32_bf16 v[100:103], v[128:131], v[168:171], v[100:103]
	v_mfma_f32_16x16x32_bf16 v[36:39], v[136:139], v[168:171], v[36:39]
	v_mfma_f32_16x16x32_bf16 v[124:127], v[132:135], v[148:151], v[124:127]
	v_mfma_f32_16x16x32_bf16 v[60:63], v[140:143], v[148:151], v[60:63]
	v_mfma_f32_16x16x32_bf16 v[116:119], v[132:135], v[156:159], v[116:119]
	v_mfma_f32_16x16x32_bf16 v[52:55], v[140:143], v[156:159], v[52:55]
	v_mfma_f32_16x16x32_bf16 v[108:111], v[132:135], v[164:167], v[108:111]
	v_mfma_f32_16x16x32_bf16 v[44:47], v[140:143], v[164:167], v[44:47]
	v_mfma_f32_16x16x32_bf16 v[100:103], v[132:135], v[172:175], v[100:103]
	v_mfma_f32_16x16x32_bf16 v[36:39], v[140:143], v[172:175], v[36:39]
	s_barrier
	s_add_i32 vcc_lo, 0, 0x14000
	v_add_u32_e32 v176, vcc_lo, v225
	s_add_i32 s77, s77, s24
	ds_read_b128 v[192:195], v176
	ds_read_b128 v[196:199], v176 offset:1024
	ds_read_b128 v[204:207], v176 offset:2048
	ds_read_b128 v[212:215], v176 offset:3072
	s_mov_b32 m0, s77
	global_load_lds_dwordx4 v182, s[70:71]
	s_add_i32 m0, s77, 0x2000
	s_nop 0
	global_load_lds_dwordx4 v186, s[70:71]
	s_barrier
	s_waitcnt lgkmcnt(0)
	s_waitcnt lgkmcnt(0)
	v_mfma_f32_16x16x32_bf16 v[120:123], v[192:195], v[144:147], v[120:123]
	v_mfma_f32_16x16x32_bf16 v[56:59], v[204:207], v[144:147], v[56:59]
	v_mfma_f32_16x16x32_bf16 v[112:115], v[192:195], v[152:155], v[112:115]
	v_mfma_f32_16x16x32_bf16 v[48:51], v[204:207], v[152:155], v[48:51]
	v_mfma_f32_16x16x32_bf16 v[104:107], v[192:195], v[160:163], v[104:107]
	v_mfma_f32_16x16x32_bf16 v[40:43], v[204:207], v[160:163], v[40:43]
	v_mfma_f32_16x16x32_bf16 v[96:99], v[192:195], v[168:171], v[96:99]
	v_mfma_f32_16x16x32_bf16 v[32:35], v[204:207], v[168:171], v[32:35]
	v_mfma_f32_16x16x32_bf16 v[120:123], v[196:199], v[148:151], v[120:123]
	v_mfma_f32_16x16x32_bf16 v[56:59], v[212:215], v[148:151], v[56:59]
	v_mfma_f32_16x16x32_bf16 v[112:115], v[196:199], v[156:159], v[112:115]
	v_mfma_f32_16x16x32_bf16 v[48:51], v[212:215], v[156:159], v[48:51]
	v_mfma_f32_16x16x32_bf16 v[104:107], v[196:199], v[164:167], v[104:107]
	v_mfma_f32_16x16x32_bf16 v[40:43], v[212:215], v[164:167], v[40:43]
	v_mfma_f32_16x16x32_bf16 v[96:99], v[196:199], v[172:175], v[96:99]
	v_mfma_f32_16x16x32_bf16 v[32:35], v[212:215], v[172:175], v[32:35]
	s_mov_b32 m0, s84
	s_mov_b64 s[100:101], s[72:73]
	s_barrier
	ds_read_b128 v[144:147], v226 offset:16384
	ds_read_b128 v[148:151], v226 offset:17408
	ds_read_b128 v[152:155], v226 offset:18432
	ds_read_b128 v[156:159], v226 offset:19456
	ds_read_b128 v[160:163], v226 offset:20480
	ds_read_b128 v[164:167], v226 offset:21504
	ds_read_b128 v[168:171], v226 offset:22528
	ds_read_b128 v[172:175], v226 offset:23552
	global_load_lds_dwordx4 v180, s[72:73]
	s_mov_b64 s[100:101], s[72:73]
	s_mov_b32 m0, s85
	s_nop 0
	global_load_lds_dwordx4 v184, s[72:73]
	s_barrier
	s_waitcnt lgkmcnt(0)
	s_waitcnt lgkmcnt(0)
	v_mfma_f32_16x16x32_bf16 v[92:95], v[128:131], v[144:147], v[92:95]
	v_mfma_f32_16x16x32_bf16 v[28:31], v[136:139], v[144:147], v[28:31]
	v_mfma_f32_16x16x32_bf16 v[84:87], v[128:131], v[152:155], v[84:87]
	v_mfma_f32_16x16x32_bf16 v[20:23], v[136:139], v[152:155], v[20:23]
	v_mfma_f32_16x16x32_bf16 v[76:79], v[128:131], v[160:163], v[76:79]
	v_mfma_f32_16x16x32_bf16 v[12:15], v[136:139], v[160:163], v[12:15]
	v_mfma_f32_16x16x32_bf16 v[68:71], v[128:131], v[168:171], v[68:71]
	v_mfma_f32_16x16x32_bf16 v[4:7], v[136:139], v[168:171], v[4:7]
	v_mfma_f32_16x16x32_bf16 v[92:95], v[132:135], v[148:151], v[92:95]
	v_mfma_f32_16x16x32_bf16 v[28:31], v[140:143], v[148:151], v[28:31]
	v_mfma_f32_16x16x32_bf16 v[84:87], v[132:135], v[156:159], v[84:87]
	v_mfma_f32_16x16x32_bf16 v[20:23], v[140:143], v[156:159], v[20:23]
	v_mfma_f32_16x16x32_bf16 v[76:79], v[132:135], v[164:167], v[76:79]
	v_mfma_f32_16x16x32_bf16 v[12:15], v[140:143], v[164:167], v[12:15]
	v_mfma_f32_16x16x32_bf16 v[68:71], v[132:135], v[172:175], v[68:71]
	v_mfma_f32_16x16x32_bf16 v[4:7], v[140:143], v[172:175], v[4:7]
	s_barrier
	s_add_u32 s78, s70, 0x80000
	s_addc_u32 s79, s71, 0
	s_add_i32 s77, vcc_lo, s24
	s_mov_b32 m0, s77
	s_nop 0
	global_load_lds_dwordx4 v182, s[78:79]
	s_add_i32 m0, s77, 0x2000
	s_nop 0
	global_load_lds_dwordx4 v186, s[78:79]
	s_waitcnt vmcnt(6)
	s_barrier
	v_mfma_f32_16x16x32_bf16 v[88:91], v[192:195], v[144:147], v[88:91]
	v_mfma_f32_16x16x32_bf16 v[24:27], v[204:207], v[144:147], v[24:27]
	v_mfma_f32_16x16x32_bf16 v[80:83], v[192:195], v[152:155], v[80:83]
	v_mfma_f32_16x16x32_bf16 v[16:19], v[204:207], v[152:155], v[16:19]
	v_mfma_f32_16x16x32_bf16 v[72:75], v[192:195], v[160:163], v[72:75]
	v_mfma_f32_16x16x32_bf16 v[8:11], v[204:207], v[160:163], v[8:11]
	v_mfma_f32_16x16x32_bf16 v[64:67], v[192:195], v[168:171], v[64:67]
	v_mfma_f32_16x16x32_bf16 v[0:3], v[204:207], v[168:171], v[0:3]
	v_mfma_f32_16x16x32_bf16 v[88:91], v[196:199], v[148:151], v[88:91]
	v_mfma_f32_16x16x32_bf16 v[24:27], v[212:215], v[148:151], v[24:27]
	v_mfma_f32_16x16x32_bf16 v[80:83], v[196:199], v[156:159], v[80:83]
	v_mfma_f32_16x16x32_bf16 v[16:19], v[212:215], v[156:159], v[16:19]
	v_mfma_f32_16x16x32_bf16 v[72:75], v[196:199], v[164:167], v[72:75]
	v_mfma_f32_16x16x32_bf16 v[8:11], v[212:215], v[164:167], v[8:11]
	v_mfma_f32_16x16x32_bf16 v[64:67], v[196:199], v[172:175], v[64:67]
	v_mfma_f32_16x16x32_bf16 v[0:3], v[212:215], v[172:175], v[0:3]
	s_add_i32 s77, 0, 0x18000
	v_add_u32_e32 v140, s77, v225
	s_barrier
	ds_read_b128 v[128:131], v140
	ds_read_b128 v[132:135], v140 offset:1024
	ds_read_b128 v[136:139], v140 offset:2048
	ds_read_b128 v[140:143], v140 offset:3072
	s_add_u32 s72, s72, 0x80000
	s_addc_u32 s73, s73, 0
	s_mov_b32 m0, s86
	ds_read_b128 v[144:147], v226 offset:32768
	ds_read_b128 v[148:151], v226 offset:33792
	ds_read_b128 v[152:155], v226 offset:34816
	ds_read_b128 v[156:159], v226 offset:35840
	ds_read_b128 v[160:163], v226 offset:36864
	ds_read_b128 v[164:167], v226 offset:37888
	ds_read_b128 v[168:171], v226 offset:38912
	ds_read_b128 v[172:175], v226 offset:39936
	global_load_lds_dwordx4 v180, s[72:73]
	s_mov_b32 m0, s87
	s_nop 0
	global_load_lds_dwordx4 v184, s[72:73]
	s_waitcnt lgkmcnt(8)
	s_barrier
	s_waitcnt lgkmcnt(0)
	s_waitcnt lgkmcnt(0)
	v_mfma_f32_16x16x32_bf16 v[124:127], v[128:131], v[144:147], v[124:127]
	v_mfma_f32_16x16x32_bf16 v[60:63], v[136:139], v[144:147], v[60:63]
	v_mfma_f32_16x16x32_bf16 v[116:119], v[128:131], v[152:155], v[116:119]
	v_mfma_f32_16x16x32_bf16 v[52:55], v[136:139], v[152:155], v[52:55]
	v_mfma_f32_16x16x32_bf16 v[108:111], v[128:131], v[160:163], v[108:111]
	v_mfma_f32_16x16x32_bf16 v[44:47], v[136:139], v[160:163], v[44:47]
	v_mfma_f32_16x16x32_bf16 v[100:103], v[128:131], v[168:171], v[100:103]
	v_mfma_f32_16x16x32_bf16 v[36:39], v[136:139], v[168:171], v[36:39]
	v_mfma_f32_16x16x32_bf16 v[124:127], v[132:135], v[148:151], v[124:127]
	v_mfma_f32_16x16x32_bf16 v[60:63], v[140:143], v[148:151], v[60:63]
	v_mfma_f32_16x16x32_bf16 v[116:119], v[132:135], v[156:159], v[116:119]
	v_mfma_f32_16x16x32_bf16 v[52:55], v[140:143], v[156:159], v[52:55]
	v_mfma_f32_16x16x32_bf16 v[108:111], v[132:135], v[164:167], v[108:111]
	v_mfma_f32_16x16x32_bf16 v[44:47], v[140:143], v[164:167], v[44:47]
	v_mfma_f32_16x16x32_bf16 v[100:103], v[132:135], v[172:175], v[100:103]
	v_mfma_f32_16x16x32_bf16 v[36:39], v[140:143], v[172:175], v[36:39]
	s_barrier
	s_add_i32 s72, 0, 0x1c000
	s_add_i32 s73, s77, s24
	v_add_u32_e32 v178, s72, v225
	s_add_i32 m0, s73, 0xffffff80
	ds_read_b128 v[192:195], v178
	ds_read_b128 v[196:199], v178 offset:1024
	ds_read_b128 v[204:207], v178 offset:2048
	ds_read_b128 v[212:215], v178 offset:3072
	global_load_lds_dwordx4 v182, s[70:71] offset:128
	s_add_i32 m0, s73, 0x1f80
	s_nop 0
	global_load_lds_dwordx4 v186, s[70:71] offset:128
	s_barrier
	s_waitcnt lgkmcnt(0)
	s_waitcnt lgkmcnt(0)
	v_mfma_f32_16x16x32_bf16 v[120:123], v[192:195], v[144:147], v[120:123]
	v_mfma_f32_16x16x32_bf16 v[56:59], v[204:207], v[144:147], v[56:59]
	v_mfma_f32_16x16x32_bf16 v[112:115], v[192:195], v[152:155], v[112:115]
	v_mfma_f32_16x16x32_bf16 v[48:51], v[204:207], v[152:155], v[48:51]
	v_mfma_f32_16x16x32_bf16 v[104:107], v[192:195], v[160:163], v[104:107]
	v_mfma_f32_16x16x32_bf16 v[40:43], v[204:207], v[160:163], v[40:43]
	v_mfma_f32_16x16x32_bf16 v[96:99], v[192:195], v[168:171], v[96:99]
	v_mfma_f32_16x16x32_bf16 v[32:35], v[204:207], v[168:171], v[32:35]
	v_mfma_f32_16x16x32_bf16 v[120:123], v[196:199], v[148:151], v[120:123]
	v_mfma_f32_16x16x32_bf16 v[56:59], v[212:215], v[148:151], v[56:59]
	v_mfma_f32_16x16x32_bf16 v[112:115], v[196:199], v[156:159], v[112:115]
	v_mfma_f32_16x16x32_bf16 v[48:51], v[212:215], v[156:159], v[48:51]
	v_mfma_f32_16x16x32_bf16 v[104:107], v[196:199], v[164:167], v[104:107]
	v_mfma_f32_16x16x32_bf16 v[40:43], v[212:215], v[164:167], v[40:43]
	v_mfma_f32_16x16x32_bf16 v[96:99], v[196:199], v[172:175], v[96:99]
	v_mfma_f32_16x16x32_bf16 v[32:35], v[212:215], v[172:175], v[32:35]
	s_add_i32 m0, s59, 0xffffff80
	s_barrier
	ds_read_b128 v[144:147], v226 offset:49152
	ds_read_b128 v[148:151], v226 offset:50176
	ds_read_b128 v[152:155], v226 offset:51200
	ds_read_b128 v[156:159], v226 offset:52224
	ds_read_b128 v[160:163], v226 offset:53248
	ds_read_b128 v[164:167], v226 offset:54272
	ds_read_b128 v[168:171], v226 offset:55296
	ds_read_b128 v[172:175], v226 offset:56320
	global_load_lds_dwordx4 v180, s[100:101] offset:128
	s_add_i32 m0, s20, 0xffffff80
	s_nop 0
	global_load_lds_dwordx4 v184, s[100:101] offset:128
	s_barrier
	s_waitcnt lgkmcnt(0)
	s_waitcnt lgkmcnt(0)
	v_mfma_f32_16x16x32_bf16 v[92:95], v[128:131], v[144:147], v[92:95]
	v_mfma_f32_16x16x32_bf16 v[28:31], v[136:139], v[144:147], v[28:31]
	v_mfma_f32_16x16x32_bf16 v[84:87], v[128:131], v[152:155], v[84:87]
	v_mfma_f32_16x16x32_bf16 v[20:23], v[136:139], v[152:155], v[20:23]
	v_mfma_f32_16x16x32_bf16 v[76:79], v[128:131], v[160:163], v[76:79]
	v_mfma_f32_16x16x32_bf16 v[12:15], v[136:139], v[160:163], v[12:15]
	v_mfma_f32_16x16x32_bf16 v[68:71], v[128:131], v[168:171], v[68:71]
	v_mfma_f32_16x16x32_bf16 v[4:7], v[136:139], v[168:171], v[4:7]
	v_mfma_f32_16x16x32_bf16 v[92:95], v[132:135], v[148:151], v[92:95]
	v_mfma_f32_16x16x32_bf16 v[28:31], v[140:143], v[148:151], v[28:31]
	v_mfma_f32_16x16x32_bf16 v[84:87], v[132:135], v[156:159], v[84:87]
	v_mfma_f32_16x16x32_bf16 v[20:23], v[140:143], v[156:159], v[20:23]
	v_mfma_f32_16x16x32_bf16 v[76:79], v[132:135], v[164:167], v[76:79]
	v_mfma_f32_16x16x32_bf16 v[12:15], v[140:143], v[164:167], v[12:15]
	v_mfma_f32_16x16x32_bf16 v[68:71], v[132:135], v[172:175], v[68:71]
	v_mfma_f32_16x16x32_bf16 v[4:7], v[140:143], v[172:175], v[4:7]
	s_barrier
	s_add_u32 s70, s70, 0x80080
	s_addc_u32 s71, s71, 0
	s_add_i32 s72, s72, s24
	s_mov_b32 m0, s72
	s_nop 0
	global_load_lds_dwordx4 v182, s[70:71]
	s_add_i32 m0, s72, 0x2000
	s_nop 0
	global_load_lds_dwordx4 v186, s[70:71]
	s_waitcnt vmcnt(6)
	s_barrier
	v_mfma_f32_16x16x32_bf16 v[88:91], v[192:195], v[144:147], v[88:91]
	v_mfma_f32_16x16x32_bf16 v[24:27], v[204:207], v[144:147], v[24:27]
	v_mfma_f32_16x16x32_bf16 v[80:83], v[192:195], v[152:155], v[80:83]
	v_mfma_f32_16x16x32_bf16 v[16:19], v[204:207], v[152:155], v[16:19]
	v_mfma_f32_16x16x32_bf16 v[72:75], v[192:195], v[160:163], v[72:75]
	v_mfma_f32_16x16x32_bf16 v[8:11], v[204:207], v[160:163], v[8:11]
	v_mfma_f32_16x16x32_bf16 v[64:67], v[192:195], v[168:171], v[64:67]
	v_mfma_f32_16x16x32_bf16 v[0:3], v[204:207], v[168:171], v[0:3]
	v_mfma_f32_16x16x32_bf16 v[88:91], v[196:199], v[148:151], v[88:91]
	v_mfma_f32_16x16x32_bf16 v[24:27], v[212:215], v[148:151], v[24:27]
	v_mfma_f32_16x16x32_bf16 v[80:83], v[196:199], v[156:159], v[80:83]
	v_mfma_f32_16x16x32_bf16 v[16:19], v[212:215], v[156:159], v[16:19]
	v_mfma_f32_16x16x32_bf16 v[72:75], v[196:199], v[164:167], v[72:75]
	v_mfma_f32_16x16x32_bf16 v[8:11], v[212:215], v[164:167], v[8:11]
	v_mfma_f32_16x16x32_bf16 v[64:67], v[196:199], v[172:175], v[64:67]
	v_mfma_f32_16x16x32_bf16 v[0:3], v[212:215], v[172:175], v[0:3]
	s_add_i32 s76, s76, 2
	s_add_u32 s35, s35, 0x100
	s_addc_u32 s75, s75, 0
	s_add_u32 s8, s8, 0x100
	s_addc_u32 s9, s9, 0
	s_cmp_gt_u32 s76, 29
	s_barrier
	s_cbranch_scc0 .LBB0_1198
	v_mov_b32_e32 v140, v224
	v_mov_b32_e32 v194, v223
	v_readlane_b32 s4, v255, 16
	v_lshlrev_b32_e32 v227, 6, v140
	v_cmp_lt_i32_e32 vcc, 14, v194
	v_add_u32_e32 v141, s4, v227
	s_mov_b64 s[4:5], 0
	s_and_saveexec_b64 s[6:7], vcc
	s_xor_b64 s[6:7], exec, s[6:7]
	s_cbranch_execz .LBB0_1203
	v_cmp_eq_u32_e32 vcc, 15, v194
	s_and_saveexec_b64 s[8:9], vcc
	s_mov_b64 s[4:5], exec
	ds_write_b128 v141, v[100:103] offset:256
	s_or_b64 exec, exec, s[8:9]
	s_and_b64 s[4:5], s[4:5], exec
